# FF1 epilogue: canonicalising v_max folded into the relu v_max (128 fewer VALU ops per unit, store-data pads kept); decode-finish pointer s_load issued with the first batch; 2-wait-state pad restored a
# baseline (speedup 1.0000x reference)
.LBB0_648:
	s_mov_b64 s[46:47], s[96:97]
	s_waitcnt lgkmcnt(0)
	s_barrier
	s_load_dwordx4 s[16:19], s[46:47], 0xd8
	s_add_u32 s42, s0, 0x28000
	s_addc_u32 s43, s1, 0
	s_lshl_b32 s35, s2, 3
	s_add_i32 s40, s93, s35
	s_cmp_lt_i32 s2, 64
	s_cbranch_scc0 .LBB0_662
	v_mbcnt_lo_u32_b32 v0, -1, 0
	v_mbcnt_hi_u32_b32 v0, -1, v0
	s_cmpk_gt_i32 s40, 0x1ff
	v_add_u32_e32 v0, s73, v0
	s_load_dwordx8 s[8:15], s[46:47], 0x50
	s_load_dwordx2 s[6:7], s[46:47], 0x70
	v_and_b32_e32 v5, 63, v0
	v_lshlrev_b32_e32 v0, 2, v5
	s_waitcnt lgkmcnt(0)
	global_load_dword v1, v0, s[8:9]
	global_load_dword v2, v0, s[10:11]
	global_load_dword v3, v0, s[12:13]
	global_load_dword v4, v0, s[14:15]
	s_waitcnt vmcnt(2)
	v_mul_f32_e32 v6, v1, v2
	s_nop 1
	v_mov_b32_dpp v6, v6 quad_perm:[1,0,3,2] row_mask:0xf bank_mask:0xf bound_ctrl:1
	s_waitcnt vmcnt(0)
	v_mul_f32_e32 v7, v3, v4
	v_fmac_f32_e32 v6, v1, v2
	s_nop 0
	v_mov_b32_dpp v7, v7 quad_perm:[1,0,3,2] row_mask:0xf bank_mask:0xf bound_ctrl:1
	v_fmac_f32_e32 v7, v3, v4
	v_add_f32_dpp v1, v6, v6 quad_perm:[2,3,0,1] row_mask:0xf bank_mask:0xf bound_ctrl:1
	s_nop 0
	v_add_f32_dpp v2, v7, v7 quad_perm:[2,3,0,1] row_mask:0xf bank_mask:0xf bound_ctrl:1
	v_add_f32_dpp v1, v1, v1 row_half_mirror row_mask:0xf bank_mask:0xf bound_ctrl:1
	s_nop 0
	v_add_f32_dpp v2, v2, v2 row_half_mirror row_mask:0xf bank_mask:0xf bound_ctrl:1
	v_add_f32_dpp v1, v1, v1 row_ror:8 row_mask:0xf bank_mask:0xf bound_ctrl:1
	v_mov_b32_e32 v3, v1
	v_add_f32_dpp v2, v2, v2 row_ror:8 row_mask:0xf bank_mask:0xf bound_ctrl:1
	v_mov_b32_e32 v4, v2
	v_permlane16_swap_b32_e32 v1, v3
	s_nop 0
	v_permlane16_swap_b32_e32 v2, v4
	v_add_f32_e32 v6, v1, v3
	v_add_f32_e32 v4, v2, v4
	v_mov_b32_e32 v8, v6
	v_mov_b32_e32 v7, v4
	s_nop 0
	v_permlane32_swap_b32_e32 v6, v8
	v_permlane32_swap_b32_e32 v4, v7
	s_cbranch_scc1 .LBB0_657
	v_lshlrev_b32_e32 v10, 3, v5
	v_add_f32_e32 v6, v6, v8
	v_add_f32_e32 v4, v4, v7
	v_mul_f32_e32 v6, 0x3fb8aa3b, v6
	s_waitcnt lgkmcnt(0)
	global_load_dwordx2 v[2:3], v10, s[6:7]
	v_mul_f32_e32 v4, 0x3fb8aa3b, v4
	s_add_u32 s14, s18, 0x29300000
	v_exp_f32_e32 v6, v6
	v_exp_f32_e32 v4, v4
	s_addc_u32 s15, s19, 0
	s_add_u32 s24, s18, 0x29400000
	v_mov_b32_e32 v1, 0
	s_addc_u32 s25, s19, 0
	s_add_u32 s26, s18, 0x8000000
	v_sub_f32_e32 v4, v6, v4
	v_lshl_add_u64 v[6:7], s[16:17], 0, v[0:1]
	s_mov_b64 s[6:7], 0x80f8000
	v_mov_b32_e32 v11, v1
	s_addc_u32 s27, s19, 0
	v_lshl_add_u64 v[6:7], v[6:7], 0, s[6:7]
	v_lshl_add_u64 v[10:11], s[16:17], 0, v[10:11]
	s_mov_b64 s[6:7], 0x8138000
	s_bfe_u32 s28, s75, 0x20006
	v_lshl_add_u64 v[10:11], v[10:11], 0, s[6:7]
	s_sub_i32 s6, 0, s28
	s_cmp_eq_u32 s28, 0
	v_cvt_f32_i32_e32 v9, s6
	s_cselect_b64 s[6:7], -1, 0
	s_sub_i32 s8, 1, s28
	s_cmp_lt_u32 s28, 2
	v_cvt_f32_i32_e32 v23, s8
	s_cselect_b64 s[8:9], -1, 0
	s_sub_i32 s10, 2, s28
	v_cvt_f32_i32_e32 v28, s10
	s_cmp_eq_u32 s28, 3
	v_add_f32_e32 v4, 0x3e4ccccd, v4
	v_lshlrev_b32_e32 v8, 1, v5
	s_cselect_b64 s[10:11], -1, 0
	s_xor_b32 s12, s28, 3
	s_mov_b32 s21, 0
	v_cvt_f32_ubyte0_e32 v29, s12
	s_or_b32 s29, s28, 4
	v_mov_b32_e32 v5, v4
	v_mov_b32_e32 v30, 0xff800000
	v_lshlrev_b32_e32 v31, 2, v8
	v_mov_b32_e32 v32, 0x358637bd
	s_mov_b32 s30, 0xf800000
	v_mov_b32_e32 v33, 0x260
	s_mov_b32 s31, 0x3f4ccccd
	s_movk_i32 s41, 0x7fff
	s_mov_b32 s72, 0xffff0000
	v_mov_b32_e32 v34, 0x3bb8aa3b
	v_mov_b32_e32 v35, 0x3cb8aa3b
	v_mov_b32_e32 v36, 1
	s_mov_b32 s75, s40
	s_branch .LBB0_652

.LBB0_832:
	v_lshl_add_u64 v[18:19], s[12:13], 0, v[12:13]
	v_add_co_u32_e32 v58, vcc, s14, v18
	v_lshl_add_u64 v[20:21], s[12:13], 0, v[16:17]
	s_nop 0
	v_addc_co_u32_e32 v59, vcc, 0, v19, vcc
	v_add_co_u32_e32 v62, vcc, s15, v18
	v_lshl_add_u64 v[34:35], s[12:13], 0, v[14:15]
	s_nop 0
	v_addc_co_u32_e32 v63, vcc, 0, v19, vcc
	s_waitcnt vmcnt(14)
	v_add_co_u32_e32 v78, vcc, s24, v18
	global_load_dwordx4 v[0:3], v[8:9], off
	global_load_dwordx4 v[4:7], v[8:9], off offset:1024
	global_load_dwordx4 v[26:29], v[8:9], off offset:2048
	global_load_dwordx4 v[30:33], v[8:9], off offset:3072
	v_addc_co_u32_e32 v79, vcc, 0, v19, vcc
	s_waitcnt vmcnt(14)
	v_add_co_u32_e32 v94, vcc, s25, v18
	s_add_i32 s8, s40, 0x4000
	s_nop 0
	v_addc_co_u32_e32 v95, vcc, 0, v19, vcc
	v_add_co_u32_e32 v20, vcc, s27, v20
	s_cmpk_lt_i32 s8, 0x4000
	s_nop 0
	v_addc_co_u32_e32 v21, vcc, 0, v21, vcc
	v_add_co_u32_e32 v18, vcc, s30, v34
	s_cselect_b32 s9, s43, 0
	s_nop 0
	v_addc_co_u32_e32 v19, vcc, 0, v35, vcc
	global_load_dwordx4 v[34:37], v[62:63], off
	global_load_dwordx4 v[38:41], v[58:59], off
	global_load_dwordx4 v[42:45], v[58:59], off offset:1024
	global_load_dwordx4 v[46:49], v[62:63], off offset:1024
	global_load_dwordx4 v[50:53], v[62:63], off offset:2048
	global_load_dwordx4 v[54:57], v[58:59], off offset:2048
	s_nop 0
	global_load_dwordx4 v[58:61], v[58:59], off offset:3072
	s_nop 0
	global_load_dwordx4 v[62:65], v[62:63], off offset:3072
	s_nop 0
	global_load_dwordx4 v[66:69], v[78:79], off
	global_load_dwordx4 v[70:73], v[78:79], off offset:1024
	global_load_dwordx4 v[74:77], v[78:79], off offset:2048
	s_nop 0
	global_load_dwordx4 v[78:81], v[78:79], off offset:3072
	s_nop 0
	global_load_dwordx4 v[82:85], v[94:95], off
	global_load_dwordx4 v[86:89], v[94:95], off offset:1024
	global_load_dwordx4 v[90:93], v[94:95], off offset:2048
	s_nop 0
	global_load_dwordx4 v[94:97], v[94:95], off offset:3072
	s_cselect_b32 s8, s42, s40
	s_cselect_b32 s31, s17, s19
	s_cselect_b32 s41, s16, s18
	s_lshl_b64 s[8:9], s[8:9], 12
	s_add_u32 s8, s41, s8
	s_addc_u32 s9, s31, s9
	global_load_dwordx4 v[98:101], v22, s[8:9]
	global_load_dwordx4 v[102:105], v22, s[8:9] offset:1024
	global_load_dwordx4 v[106:109], v22, s[8:9] offset:2048
	global_load_dwordx4 v[110:113], v22, s[8:9] offset:3072
	global_load_dwordx4 v[114:117], v[10:11], off
	global_load_dwordx4 v[118:121], v[10:11], off offset:1024
	global_load_dwordx4 v[122:125], v[10:11], off offset:2048
	global_load_dwordx4 v[126:129], v[10:11], off offset:3072
	s_add_i32 s40, s40, s34
	v_lshl_add_u64 v[12:13], v[12:13], 0, s[44:45]
	v_lshl_add_u64 v[14:15], v[14:15], 0, s[46:47]
	v_lshl_add_u64 v[16:17], v[16:17], 0, s[44:45]
	s_waitcnt vmcnt(22)
	v_pk_add_f32 v[36:37], v[40:41], v[36:37]
	v_pk_add_f32 v[34:35], v[38:39], v[34:35]
	s_waitcnt vmcnt(20)
	v_pk_add_f32 v[38:39], v[44:45], v[48:49]
	v_pk_add_f32 v[40:41], v[42:43], v[46:47]
	s_waitcnt vmcnt(18)
	v_pk_add_f32 v[42:43], v[56:57], v[52:53]
	v_pk_add_f32 v[44:45], v[54:55], v[50:51]
	s_waitcnt vmcnt(16)
	v_pk_add_f32 v[46:47], v[60:61], v[64:65]
	s_waitcnt vmcnt(15)
	v_pk_add_f32 v[36:37], v[36:37], v[68:69]
	v_pk_add_f32 v[34:35], v[34:35], v[66:67]
	s_waitcnt vmcnt(14)
	v_pk_add_f32 v[38:39], v[38:39], v[72:73]
	v_pk_add_f32 v[40:41], v[40:41], v[70:71]
	v_pk_add_f32 v[48:49], v[58:59], v[62:63]
	s_waitcnt vmcnt(13)
	v_pk_add_f32 v[42:43], v[42:43], v[76:77]
	v_pk_add_f32 v[44:45], v[44:45], v[74:75]
	s_waitcnt vmcnt(11)
	v_pk_add_f32 v[36:37], v[36:37], v[84:85]
	v_pk_add_f32 v[34:35], v[34:35], v[82:83]
	s_waitcnt vmcnt(10)
	v_pk_add_f32 v[38:39], v[38:39], v[88:89]
	v_pk_add_f32 v[40:41], v[40:41], v[86:87]
	v_pk_add_f32 v[46:47], v[46:47], v[80:81]
	v_pk_add_f32 v[48:49], v[48:49], v[78:79]
	s_waitcnt vmcnt(9)
	v_pk_add_f32 v[42:43], v[42:43], v[92:93]
	v_pk_add_f32 v[44:45], v[44:45], v[90:91]
	v_mul_f32_e32 v25, v35, v35
	v_mul_f32_e32 v50, v37, v37
	v_mul_f32_e32 v51, v41, v41
	v_mul_f32_e32 v52, v39, v39
	s_waitcnt vmcnt(8)
	v_pk_add_f32 v[46:47], v[46:47], v[96:97]
	v_pk_add_f32 v[48:49], v[48:49], v[94:95]
	v_mul_f32_e32 v53, v45, v45
	v_mul_f32_e32 v54, v43, v43
	v_fmac_f32_e32 v25, v34, v34
	v_fmac_f32_e32 v50, v36, v36
	v_fmac_f32_e32 v51, v40, v40
	v_fmac_f32_e32 v52, v38, v38
	v_mul_f32_e32 v55, v49, v49
	v_mul_f32_e32 v56, v47, v47
	v_fmac_f32_e32 v53, v44, v44
	v_fmac_f32_e32 v54, v42, v42
	v_add_f32_e32 v25, v25, v50
	v_add_f32_e32 v50, v51, v52
	v_fmac_f32_e32 v55, v48, v48
	v_fmac_f32_e32 v56, v46, v46
	v_add_f32_e32 v51, v53, v54
	v_add_f32_e32 v25, v25, v50
	v_add_f32_e32 v52, v55, v56
	v_add_f32_e32 v25, v25, v51
	v_add_f32_e32 v25, v25, v52
	s_nop 1
	v_add_f32_dpp v25, v25, v25 quad_perm:[1,0,3,2] row_mask:0xf bank_mask:0xf bound_ctrl:1
	s_nop 1
	v_add_f32_dpp v25, v25, v25 quad_perm:[2,3,0,1] row_mask:0xf bank_mask:0xf bound_ctrl:1
	s_nop 1
	v_add_f32_dpp v25, v25, v25 row_half_mirror row_mask:0xf bank_mask:0xf bound_ctrl:1
	s_nop 1
	v_add_f32_dpp v25, v25, v25 row_ror:8 row_mask:0xf bank_mask:0xf bound_ctrl:1
	v_mov_b32_e32 v50, v25
	s_nop 1
	v_permlane16_swap_b32_e32 v25, v50
	v_add_f32_e32 v25, v25, v50
	v_mov_b32_e32 v50, v25
	s_nop 1
	v_permlane32_swap_b32_e32 v25, v50
	v_add_f32_e32 v25, v25, v50
	v_fmamk_f32 v25, v25, 0x3a800000, v23
	v_mul_f32_e32 v50, 0x4f800000, v25
	v_cmp_gt_f32_e32 vcc, s26, v25
	s_nop 1
	v_cndmask_b32_e32 v25, v25, v50, vcc
	v_sqrt_f32_e32 v50, v25
	s_nop 0
	v_add_u32_e32 v51, -1, v50
	v_add_u32_e32 v52, 1, v50
	v_fma_f32 v53, -v51, v50, v25
	v_fma_f32 v54, -v52, v50, v25
	v_cmp_ge_f32_e64 s[8:9], 0, v53
	s_nop 1
	v_cndmask_b32_e64 v50, v50, v51, s[8:9]
	v_cmp_lt_f32_e64 s[8:9], 0, v54
	s_nop 1
	v_cndmask_b32_e64 v50, v50, v52, s[8:9]
	v_mul_f32_e32 v51, 0x37800000, v50
	v_cndmask_b32_e32 v50, v50, v51, vcc
	v_cmp_class_f32_e32 vcc, v25, v24
	s_nop 1
	v_cndmask_b32_e32 v25, v50, v25, vcc
	v_div_scale_f32 v50, s[8:9], v25, v25, 1.0
	v_rcp_f32_e32 v52, v50
	v_div_scale_f32 v51, vcc, 1.0, v25, 1.0
	v_fma_f32 v53, -v50, v52, 1.0
	v_fmac_f32_e32 v52, v53, v52
	v_mul_f32_e32 v53, v51, v52
	v_fma_f32 v54, -v50, v53, v51
	v_fmac_f32_e32 v53, v54, v52
	v_fma_f32 v50, -v50, v53, v51
	v_div_fmas_f32 v50, v50, v52, v53
	v_div_fixup_f32 v50, v50, v25, 1.0
	v_pk_mul_f32 v[34:35], v[34:35], v[50:51] op_sel_hi:[1,0]
	v_pk_mul_f32 v[36:37], v[36:37], v[50:51] op_sel_hi:[1,0]
	s_waitcnt vmcnt(7)
	v_pk_fma_f32 v[0:1], v[0:1], v[34:35], v[98:99]
	v_pk_fma_f32 v[2:3], v[2:3], v[36:37], v[100:101]
	global_store_dwordx4 v[20:21], v[0:3], off sc1
	v_pk_mul_f32 v[40:41], v[40:41], v[50:51] op_sel_hi:[1,0]
	v_pk_mul_f32 v[38:39], v[38:39], v[50:51] op_sel_hi:[1,0]
	v_pk_mul_f32 v[44:45], v[44:45], v[50:51] op_sel_hi:[1,0]
	v_pk_mul_f32 v[42:43], v[42:43], v[50:51] op_sel_hi:[1,0]
	s_waitcnt vmcnt(7)
	v_pk_fma_f32 v[6:7], v[6:7], v[38:39], v[104:105]
	v_pk_fma_f32 v[4:5], v[4:5], v[40:41], v[102:103]
	v_pk_mul_f32 v[48:49], v[48:49], v[50:51] op_sel_hi:[1,0]
	v_pk_mul_f32 v[46:47], v[46:47], v[50:51] op_sel_hi:[1,0]
	s_waitcnt vmcnt(6)
	v_pk_fma_f32 v[28:29], v[28:29], v[42:43], v[108:109]
	v_pk_fma_f32 v[26:27], v[26:27], v[44:45], v[106:107]
	v_mul_f32_e32 v25, v1, v1
	v_mul_f32_e32 v38, v3, v3
	v_mul_f32_e32 v39, v5, v5
	v_mul_f32_e32 v40, v7, v7
	s_waitcnt vmcnt(5)
	v_pk_fma_f32 v[32:33], v[32:33], v[46:47], v[112:113]
	v_pk_fma_f32 v[30:31], v[30:31], v[48:49], v[110:111]
	v_mul_f32_e32 v41, v27, v27
	v_mul_f32_e32 v42, v29, v29
	v_fmac_f32_e32 v25, v0, v0
	v_fmac_f32_e32 v38, v2, v2
	v_fmac_f32_e32 v39, v4, v4
	v_fmac_f32_e32 v40, v6, v6
	v_mul_f32_e32 v43, v31, v31
	v_mul_f32_e32 v44, v33, v33
	v_fmac_f32_e32 v41, v26, v26
	v_fmac_f32_e32 v42, v28, v28
	v_add_f32_e32 v25, v25, v38
	v_add_f32_e32 v38, v39, v40
	v_fmac_f32_e32 v43, v30, v30
	v_fmac_f32_e32 v44, v32, v32
	v_add_f32_e32 v39, v41, v42
	v_add_f32_e32 v25, v25, v38
	v_add_f32_e32 v40, v43, v44
	v_add_f32_e32 v25, v39, v25
	v_add_f32_e32 v25, v40, v25
	s_nop 1
	v_add_f32_dpp v25, v25, v25 quad_perm:[1,0,3,2] row_mask:0xf bank_mask:0xf bound_ctrl:1
	s_nop 1
	v_add_f32_dpp v25, v25, v25 quad_perm:[2,3,0,1] row_mask:0xf bank_mask:0xf bound_ctrl:1
	s_nop 1
	v_add_f32_dpp v25, v25, v25 row_half_mirror row_mask:0xf bank_mask:0xf bound_ctrl:1
	s_nop 1
	v_add_f32_dpp v25, v25, v25 row_ror:8 row_mask:0xf bank_mask:0xf bound_ctrl:1
	v_mov_b32_e32 v38, v25
	s_nop 1
	v_permlane16_swap_b32_e32 v25, v38
	v_add_f32_e32 v25, v25, v38
	v_mov_b32_e32 v38, v25
	s_nop 1
	v_permlane32_swap_b32_e32 v25, v38
	v_add_f32_e32 v25, v25, v38
	v_fmamk_f32 v25, v25, 0x3a800000, v23
	v_mul_f32_e32 v38, 0x4f800000, v25
	v_cmp_gt_f32_e32 vcc, s26, v25
	s_nop 1
	v_cndmask_b32_e32 v25, v25, v38, vcc
	v_sqrt_f32_e32 v38, v25
	s_nop 0
	v_add_u32_e32 v39, -1, v38
	v_add_u32_e32 v40, 1, v38
	v_fma_f32 v41, -v39, v38, v25
	v_fma_f32 v42, -v40, v38, v25
	v_cmp_ge_f32_e64 s[8:9], 0, v41
	s_nop 1
	v_cndmask_b32_e64 v38, v38, v39, s[8:9]
	v_cmp_lt_f32_e64 s[8:9], 0, v42
	s_nop 1
	v_cndmask_b32_e64 v38, v38, v40, s[8:9]
	v_mul_f32_e32 v39, 0x37800000, v38
	v_cndmask_b32_e32 v38, v38, v39, vcc
	v_cmp_class_f32_e32 vcc, v25, v24
	s_nop 1
	v_cndmask_b32_e32 v25, v38, v25, vcc
	v_div_scale_f32 v38, s[8:9], v25, v25, 1.0
	v_rcp_f32_e32 v40, v38
	v_div_scale_f32 v39, vcc, 1.0, v25, 1.0
	s_add_i32 s8, s40, 0x4000
	v_fma_f32 v41, -v38, v40, 1.0
	v_fmac_f32_e32 v40, v41, v40
	v_mul_f32_e32 v41, v39, v40
	v_fma_f32 v42, -v38, v41, v39
	v_fmac_f32_e32 v41, v42, v40
	v_fma_f32 v38, -v38, v41, v39
	v_div_fmas_f32 v38, v38, v40, v41
	v_div_fixup_f32 v25, v38, v25, 1.0
	v_mul_f32_e32 v0, v0, v25
	v_mul_f32_e32 v2, v2, v25
	v_mul_f32_e32 v1, v1, v25
	v_mul_f32_e32 v3, v3, v25
	s_waitcnt vmcnt(4)
	v_mul_f32_e32 v0, v114, v0
	v_mul_f32_e32 v2, v116, v2
	v_mul_f32_e32 v1, v115, v1
	v_mul_f32_e32 v3, v117, v3
	v_bfe_u32 v34, v0, 16, 1
	v_bfe_u32 v36, v2, 16, 1
	v_bfe_u32 v35, v1, 16, 1
	v_bfe_u32 v37, v3, 16, 1
	v_add3_u32 v0, v0, v34, s28
	v_add3_u32 v2, v2, v36, s28
	v_add3_u32 v1, v1, v35, s28
	v_add3_u32 v3, v3, v37, s28
	v_lshrrev_b32_e32 v0, 16, v0
	v_lshrrev_b32_e32 v2, 16, v2
	v_and_or_b32 v0, v1, s29, v0
	v_and_or_b32 v1, v3, s29, v2
	global_store_dwordx2 v[18:19], v[0:1], off sc1
	global_store_dwordx4 v[20:21], v[4:7], off offset:1024 sc1
	s_nop 0
	s_add_u32 s42, s42, s34
	v_mul_f32_e32 v4, v4, v25
	v_mul_f32_e32 v6, v6, v25
	v_mul_f32_e32 v5, v5, v25
	v_mul_f32_e32 v7, v7, v25
	s_addc_u32 s43, s43, s35
	s_cmpk_gt_i32 s8, 0x407f
	s_waitcnt vmcnt(5)
	v_mul_f32_e32 v0, v118, v4
	v_mul_f32_e32 v2, v120, v6
	v_mul_f32_e32 v1, v119, v5
	v_mul_f32_e32 v3, v121, v7
	v_bfe_u32 v4, v0, 16, 1
	v_bfe_u32 v6, v2, 16, 1
	v_bfe_u32 v5, v1, 16, 1
	v_bfe_u32 v7, v3, 16, 1
	v_add3_u32 v0, v0, v4, s28
	v_add3_u32 v2, v2, v6, s28
	v_add3_u32 v1, v1, v5, s28
	v_add3_u32 v3, v3, v7, s28
	v_lshrrev_b32_e32 v0, 16, v0
	v_lshrrev_b32_e32 v2, 16, v2
	v_and_or_b32 v0, v1, s29, v0
	v_and_or_b32 v1, v3, s29, v2
	global_store_dwordx2 v[18:19], v[0:1], off offset:512 sc1
	global_store_dwordx4 v[20:21], v[26:29], off offset:2048 sc1
	v_mul_f32_e32 v4, v26, v25
	v_mul_f32_e32 v6, v28, v25
	v_mul_f32_e32 v5, v27, v25
	v_mul_f32_e32 v7, v29, v25
	s_waitcnt vmcnt(6)
	v_mul_f32_e32 v0, v4, v122
	v_mul_f32_e32 v2, v6, v124
	v_mul_f32_e32 v1, v5, v123
	v_mul_f32_e32 v3, v7, v125
	v_bfe_u32 v4, v0, 16, 1
	v_bfe_u32 v6, v2, 16, 1
	v_bfe_u32 v5, v1, 16, 1
	v_bfe_u32 v7, v3, 16, 1
	v_add3_u32 v0, v0, v4, s28
	v_add3_u32 v2, v2, v6, s28
	v_add3_u32 v1, v1, v5, s28
	v_add3_u32 v3, v3, v7, s28
	v_lshrrev_b32_e32 v0, 16, v0
	v_lshrrev_b32_e32 v2, 16, v2
	v_and_or_b32 v0, v1, s29, v0
	v_and_or_b32 v1, v3, s29, v2
	global_store_dwordx2 v[18:19], v[0:1], off offset:1024 sc1
	global_store_dwordx4 v[20:21], v[30:33], off offset:3072 sc1
	v_mul_f32_e32 v4, v30, v25
	v_mul_f32_e32 v6, v32, v25
	v_mul_f32_e32 v5, v31, v25
	v_mul_f32_e32 v7, v33, v25
	s_waitcnt vmcnt(7)
	v_mul_f32_e32 v0, v4, v126
	v_mul_f32_e32 v2, v6, v128
	v_mul_f32_e32 v1, v5, v127
	v_mul_f32_e32 v3, v7, v129
	v_bfe_u32 v4, v0, 16, 1
	v_bfe_u32 v6, v2, 16, 1
	v_bfe_u32 v5, v1, 16, 1
	v_bfe_u32 v7, v3, 16, 1
	v_add3_u32 v0, v0, v4, s28
	v_add3_u32 v2, v2, v6, s28
	v_add3_u32 v1, v1, v5, s28
	v_add3_u32 v3, v3, v7, s28
	v_lshrrev_b32_e32 v0, 16, v0
	v_lshrrev_b32_e32 v2, 16, v2
	v_and_or_b32 v0, v1, s29, v0
	v_and_or_b32 v1, v3, s29, v2
	global_store_dwordx2 v[18:19], v[0:1], off offset:1536 sc1
	s_cbranch_scc0 .LBB0_832

.LBB0_859:
	v_lshl_add_u32 v152, s80, 8, v146
	v_lshl_or_b32 v144, s81, 8, v148
	v_ashrrev_i32_e32 v153, 31, v152
	v_max_f32_e32 v120, 0, v120
	v_ashrrev_i32_e32 v145, 31, v144
	v_lshlrev_b64 v[154:155], 13, v[152:153]
	v_max_f32_e32 v121, 0, v121
	v_max_f32_e32 v122, 0, v122
	v_max_f32_e32 v123, 0, v123
	v_lshl_add_u64 v[154:155], s[16:17], 0, v[154:155]
	v_lshlrev_b64 v[156:157], 1, v[144:145]
	v_max_f32_e32 v124, 0, v124
	v_mul_f32_e32 v120, v120, v120
	v_max_f32_e32 v125, 0, v125
	v_max_f32_e32 v126, 0, v126
	v_max_f32_e32 v127, 0, v127
	v_max_f32_e32 v112, 0, v112
	v_lshl_add_u64 v[144:145], v[154:155], 0, v[156:157]
	v_mul_f32_e32 v121, v121, v121
	v_mul_f32_e32 v122, v122, v122
	v_mul_f32_e32 v123, v123, v123
	v_cvt_pk_bf16_f32 v120, v120, v121
	v_max_f32_e32 v113, 0, v113
	v_max_f32_e32 v114, 0, v114
	v_mul_f32_e32 v124, v124, v124
	v_mul_f32_e32 v125, v125, v125
	v_mul_f32_e32 v126, v126, v126
	v_mul_f32_e32 v127, v127, v127
	v_cvt_pk_bf16_f32 v121, v122, v123
	v_cvt_pk_bf16_f32 v122, v124, v125
	v_cvt_pk_bf16_f32 v123, v126, v127
	global_store_dwordx4 v[144:145], v[120:123], off
	s_nop 1
	v_mul_f32_e32 v120, v112, v112
	v_max_f32_e32 v112, 0, v117
	v_max_f32_e32 v116, 0, v116
	v_mul_f32_e32 v117, v113, v113
	v_max_f32_e32 v113, 0, v118
	v_mul_f32_e32 v118, v114, v114
	v_max_f32_e32 v114, 0, v119
	v_max_f32_e32 v115, 0, v115
	v_mul_f32_e32 v112, v112, v112
	v_mul_f32_e32 v116, v116, v116
	v_mul_f32_e32 v113, v113, v113
	v_mul_f32_e32 v114, v114, v114
	v_mul_f32_e32 v115, v115, v115
	v_cvt_pk_bf16_f32 v112, v116, v112
	v_max_f32_e32 v104, 0, v104
	v_cvt_pk_bf16_f32 v113, v113, v114
	v_cvt_pk_bf16_f32 v114, v120, v117
	v_cvt_pk_bf16_f32 v115, v118, v115
	global_store_dwordx4 v[144:145], v[112:115], off offset:256
	s_nop 1
	v_max_f32_e32 v105, 0, v105
	v_or_b32_e32 v112, 16, v152
	v_max_f32_e32 v106, 0, v106
	v_ashrrev_i32_e32 v113, 31, v112
	v_mul_f32_e32 v114, v104, v104
	v_max_f32_e32 v104, 0, v109
	v_lshlrev_b64 v[112:113], 13, v[112:113]
	v_max_f32_e32 v108, 0, v108
	v_mul_f32_e32 v109, v105, v105
	v_max_f32_e32 v105, 0, v110
	v_mul_f32_e32 v110, v106, v106
	v_max_f32_e32 v106, 0, v111
	v_max_f32_e32 v107, 0, v107
	v_lshl_add_u64 v[112:113], s[16:17], 0, v[112:113]
	v_mul_f32_e32 v104, v104, v104
	v_max_f32_e32 v96, 0, v96
	v_lshl_add_u64 v[112:113], v[112:113], 0, v[156:157]
	v_mul_f32_e32 v108, v108, v108
	v_mul_f32_e32 v105, v105, v105
	v_mul_f32_e32 v106, v106, v106
	v_mul_f32_e32 v107, v107, v107
	v_cvt_pk_bf16_f32 v104, v108, v104
	v_max_f32_e32 v97, 0, v97
	v_max_f32_e32 v98, 0, v98
	v_cvt_pk_bf16_f32 v105, v105, v106
	v_cvt_pk_bf16_f32 v106, v114, v109
	v_cvt_pk_bf16_f32 v107, v110, v107
	global_store_dwordx4 v[112:113], v[104:107], off
	s_nop 1
	v_mul_f32_e32 v104, v96, v96
	v_max_f32_e32 v96, 0, v101
	v_max_f32_e32 v100, 0, v100
	v_mul_f32_e32 v101, v97, v97
	v_max_f32_e32 v97, 0, v102
	v_mul_f32_e32 v102, v98, v98
	v_max_f32_e32 v98, 0, v103
	v_max_f32_e32 v99, 0, v99
	v_mul_f32_e32 v96, v96, v96
	v_mul_f32_e32 v100, v100, v100
	v_mul_f32_e32 v97, v97, v97
	v_mul_f32_e32 v98, v98, v98
	v_mul_f32_e32 v99, v99, v99
	v_cvt_pk_bf16_f32 v96, v100, v96
	v_max_f32_e32 v88, 0, v88
	v_cvt_pk_bf16_f32 v97, v97, v98
	v_cvt_pk_bf16_f32 v98, v104, v101
	v_cvt_pk_bf16_f32 v99, v102, v99
	global_store_dwordx4 v[112:113], v[96:99], off offset:256
	s_nop 1
	v_max_f32_e32 v89, 0, v89
	v_or_b32_e32 v96, 32, v152
	v_max_f32_e32 v90, 0, v90
	v_ashrrev_i32_e32 v97, 31, v96
	v_mul_f32_e32 v98, v88, v88
	v_max_f32_e32 v88, 0, v93
	v_lshlrev_b64 v[96:97], 13, v[96:97]
	v_max_f32_e32 v92, 0, v92
	v_mul_f32_e32 v93, v89, v89
	v_max_f32_e32 v89, 0, v94
	v_mul_f32_e32 v94, v90, v90
	v_max_f32_e32 v90, 0, v95
	v_max_f32_e32 v91, 0, v91
	v_lshl_add_u64 v[96:97], s[16:17], 0, v[96:97]
	v_mul_f32_e32 v88, v88, v88
	v_max_f32_e32 v80, 0, v80
	v_lshl_add_u64 v[96:97], v[96:97], 0, v[156:157]
	v_mul_f32_e32 v92, v92, v92
	v_mul_f32_e32 v89, v89, v89
	v_mul_f32_e32 v90, v90, v90
	v_mul_f32_e32 v91, v91, v91
	v_cvt_pk_bf16_f32 v88, v92, v88
	v_max_f32_e32 v81, 0, v81
	v_max_f32_e32 v82, 0, v82
	v_cvt_pk_bf16_f32 v89, v89, v90
	v_cvt_pk_bf16_f32 v90, v98, v93
	v_cvt_pk_bf16_f32 v91, v94, v91
	global_store_dwordx4 v[96:97], v[88:91], off
	s_nop 1
	v_mul_f32_e32 v88, v80, v80
	v_max_f32_e32 v80, 0, v85
	v_max_f32_e32 v84, 0, v84
	v_mul_f32_e32 v85, v81, v81
	v_max_f32_e32 v81, 0, v86
	v_mul_f32_e32 v86, v82, v82
	v_max_f32_e32 v82, 0, v87
	v_max_f32_e32 v83, 0, v83
	v_mul_f32_e32 v80, v80, v80
	v_mul_f32_e32 v84, v84, v84
	v_mul_f32_e32 v81, v81, v81
	v_mul_f32_e32 v82, v82, v82
	v_mul_f32_e32 v83, v83, v83
	v_cvt_pk_bf16_f32 v80, v84, v80
	v_max_f32_e32 v72, 0, v72
	v_cvt_pk_bf16_f32 v81, v81, v82
	v_cvt_pk_bf16_f32 v82, v88, v85
	v_cvt_pk_bf16_f32 v83, v86, v83
	global_store_dwordx4 v[96:97], v[80:83], off offset:256
	s_nop 1
	v_max_f32_e32 v73, 0, v73
	v_or_b32_e32 v80, 48, v152
	v_max_f32_e32 v74, 0, v74
	v_ashrrev_i32_e32 v81, 31, v80
	v_mul_f32_e32 v82, v72, v72
	v_max_f32_e32 v72, 0, v77
	v_lshlrev_b64 v[80:81], 13, v[80:81]
	v_max_f32_e32 v76, 0, v76
	v_mul_f32_e32 v77, v73, v73
	v_max_f32_e32 v73, 0, v78
	v_mul_f32_e32 v78, v74, v74
	v_max_f32_e32 v74, 0, v79
	v_max_f32_e32 v75, 0, v75
	v_lshl_add_u64 v[80:81], s[16:17], 0, v[80:81]
	v_mul_f32_e32 v72, v72, v72
	v_max_f32_e32 v64, 0, v64
	v_max_f32_e32 v65, 0, v65
	v_max_f32_e32 v66, 0, v66
	v_lshl_add_u64 v[80:81], v[80:81], 0, v[156:157]
	v_mul_f32_e32 v76, v76, v76
	v_mul_f32_e32 v73, v73, v73
	v_mul_f32_e32 v74, v74, v74
	v_mul_f32_e32 v75, v75, v75
	v_cvt_pk_bf16_f32 v72, v76, v72
	v_cvt_pk_bf16_f32 v73, v73, v74
	v_cvt_pk_bf16_f32 v74, v82, v77
	v_cvt_pk_bf16_f32 v75, v78, v75
	global_store_dwordx4 v[80:81], v[72:75], off
	v_max_f32_e32 v68, 0, v68
	v_max_f32_e32 v67, 0, v67
	v_mul_f32_e32 v72, v64, v64
	v_max_f32_e32 v64, 0, v69
	v_mul_f32_e32 v69, v65, v65
	v_max_f32_e32 v65, 0, v70
	v_mul_f32_e32 v70, v66, v66
	v_max_f32_e32 v66, 0, v71
	v_mul_f32_e32 v64, v64, v64
	v_mul_f32_e32 v65, v65, v65
	v_mul_f32_e32 v66, v66, v66
	v_max_f32_e32 v56, 0, v56
	v_mul_f32_e32 v68, v68, v68
	v_mul_f32_e32 v67, v67, v67
	v_cvt_pk_bf16_f32 v64, v68, v64
	v_cvt_pk_bf16_f32 v65, v65, v66
	v_cvt_pk_bf16_f32 v66, v72, v69
	v_max_f32_e32 v57, 0, v57
	v_max_f32_e32 v58, 0, v58
	v_cvt_pk_bf16_f32 v67, v70, v67
	global_store_dwordx4 v[80:81], v[64:67], off offset:256
	s_nop 1
	v_max_f32_e32 v60, 0, v60
	v_mul_f32_e32 v66, v56, v56
	v_max_f32_e32 v56, 0, v61
	v_mul_f32_e32 v61, v57, v57
	v_max_f32_e32 v57, 0, v62
	v_mul_f32_e32 v62, v58, v58
	v_max_f32_e32 v58, 0, v63
	v_mul_f32_e32 v60, v60, v60
	v_mul_f32_e32 v56, v56, v56
	v_max_f32_e32 v59, 0, v59
	v_mul_f32_e32 v57, v57, v57
	v_mul_f32_e32 v58, v58, v58
	v_cvt_pk_bf16_f32 v56, v60, v56
	v_add_co_u32_e32 v60, vcc, s69, v144
	v_max_f32_e32 v48, 0, v48
	v_max_f32_e32 v49, 0, v49
	v_max_f32_e32 v50, 0, v50
	v_mul_f32_e32 v59, v59, v59
	v_cvt_pk_bf16_f32 v57, v57, v58
	v_cvt_pk_bf16_f32 v58, v66, v61
	v_addc_co_u32_e32 v61, vcc, 0, v145, vcc
	v_cvt_pk_bf16_f32 v59, v62, v59
	global_store_dwordx4 v[60:61], v[56:59], off
	v_max_f32_e32 v52, 0, v52
	v_max_f32_e32 v51, 0, v51
	v_mul_f32_e32 v56, v48, v48
	v_max_f32_e32 v48, 0, v53
	v_mul_f32_e32 v53, v49, v49
	v_max_f32_e32 v49, 0, v54
	v_mul_f32_e32 v54, v50, v50
	v_max_f32_e32 v50, 0, v55
	v_mul_f32_e32 v48, v48, v48
	v_mul_f32_e32 v49, v49, v49
	v_mul_f32_e32 v50, v50, v50
	v_max_f32_e32 v40, 0, v40
	v_lshl_add_u64 v[64:65], v[144:145], 0, s[50:51]
	v_mul_f32_e32 v52, v52, v52
	v_mul_f32_e32 v51, v51, v51
	v_cvt_pk_bf16_f32 v48, v52, v48
	v_cvt_pk_bf16_f32 v49, v49, v50
	v_cvt_pk_bf16_f32 v50, v56, v53
	v_max_f32_e32 v41, 0, v41
	v_max_f32_e32 v42, 0, v42
	v_cvt_pk_bf16_f32 v51, v54, v51
	global_store_dwordx4 v[64:65], v[48:51], off offset:256
	s_nop 1
	v_max_f32_e32 v44, 0, v44
	v_mul_f32_e32 v50, v40, v40
	v_max_f32_e32 v40, 0, v45
	v_mul_f32_e32 v45, v41, v41
	v_max_f32_e32 v41, 0, v46
	v_mul_f32_e32 v46, v42, v42
	v_max_f32_e32 v42, 0, v47
	v_mul_f32_e32 v44, v44, v44
	v_mul_f32_e32 v40, v40, v40
	v_max_f32_e32 v43, 0, v43
	v_mul_f32_e32 v41, v41, v41
	v_mul_f32_e32 v42, v42, v42
	v_cvt_pk_bf16_f32 v40, v44, v40
	v_add_co_u32_e32 v44, vcc, s71, v144
	v_max_f32_e32 v32, 0, v32
	v_max_f32_e32 v33, 0, v33
	v_max_f32_e32 v34, 0, v34
	v_mul_f32_e32 v43, v43, v43
	v_cvt_pk_bf16_f32 v41, v41, v42
	v_cvt_pk_bf16_f32 v42, v50, v45
	v_addc_co_u32_e32 v45, vcc, 0, v145, vcc
	v_cvt_pk_bf16_f32 v43, v46, v43
	global_store_dwordx4 v[44:45], v[40:43], off
	v_max_f32_e32 v36, 0, v36
	v_max_f32_e32 v35, 0, v35
	v_mul_f32_e32 v40, v32, v32
	v_max_f32_e32 v32, 0, v37
	v_mul_f32_e32 v37, v33, v33
	v_max_f32_e32 v33, 0, v38
	v_mul_f32_e32 v38, v34, v34
	v_max_f32_e32 v34, 0, v39
	v_mul_f32_e32 v32, v32, v32
	v_mul_f32_e32 v33, v33, v33
	v_mul_f32_e32 v34, v34, v34
	v_max_f32_e32 v24, 0, v24
	v_lshl_add_u64 v[48:49], v[144:145], 0, s[52:53]
	v_mul_f32_e32 v36, v36, v36
	v_mul_f32_e32 v35, v35, v35
	v_cvt_pk_bf16_f32 v32, v36, v32
	v_cvt_pk_bf16_f32 v33, v33, v34
	v_cvt_pk_bf16_f32 v34, v40, v37
	v_max_f32_e32 v25, 0, v25
	v_max_f32_e32 v26, 0, v26
	v_cvt_pk_bf16_f32 v35, v38, v35
	global_store_dwordx4 v[48:49], v[32:35], off offset:256
	s_nop 1
	v_max_f32_e32 v28, 0, v28
	v_mul_f32_e32 v34, v24, v24
	v_max_f32_e32 v24, 0, v29
	v_mul_f32_e32 v29, v25, v25
	v_max_f32_e32 v25, 0, v30
	v_mul_f32_e32 v30, v26, v26
	v_max_f32_e32 v26, 0, v31
	v_mul_f32_e32 v28, v28, v28
	v_mul_f32_e32 v24, v24, v24
	v_max_f32_e32 v27, 0, v27
	v_mul_f32_e32 v25, v25, v25
	v_mul_f32_e32 v26, v26, v26
	v_cvt_pk_bf16_f32 v24, v28, v24
	v_add_co_u32_e32 v28, vcc, s72, v144
	v_max_f32_e32 v16, 0, v16
	v_max_f32_e32 v17, 0, v17
	v_max_f32_e32 v18, 0, v18
	v_mul_f32_e32 v27, v27, v27
	v_cvt_pk_bf16_f32 v25, v25, v26
	v_cvt_pk_bf16_f32 v26, v34, v29
	v_addc_co_u32_e32 v29, vcc, 0, v145, vcc
	v_cvt_pk_bf16_f32 v27, v30, v27
	global_store_dwordx4 v[28:29], v[24:27], off
	v_max_f32_e32 v20, 0, v20
	v_max_f32_e32 v19, 0, v19
	v_mul_f32_e32 v24, v16, v16
	v_max_f32_e32 v16, 0, v21
	v_mul_f32_e32 v21, v17, v17
	v_max_f32_e32 v17, 0, v22
	v_mul_f32_e32 v22, v18, v18
	v_max_f32_e32 v18, 0, v23
	v_mul_f32_e32 v16, v16, v16
	v_mul_f32_e32 v17, v17, v17
	v_mul_f32_e32 v18, v18, v18
	v_max_f32_e32 v8, 0, v8
	v_lshl_add_u64 v[32:33], v[144:145], 0, s[54:55]
	v_mul_f32_e32 v20, v20, v20
	v_mul_f32_e32 v19, v19, v19
	v_cvt_pk_bf16_f32 v16, v20, v16
	v_cvt_pk_bf16_f32 v17, v17, v18
	v_cvt_pk_bf16_f32 v18, v24, v21
	v_max_f32_e32 v9, 0, v9
	v_max_f32_e32 v10, 0, v10
	v_cvt_pk_bf16_f32 v19, v22, v19
	global_store_dwordx4 v[32:33], v[16:19], off offset:256
	s_nop 1
	v_max_f32_e32 v12, 0, v12
	v_mul_f32_e32 v18, v8, v8
	v_max_f32_e32 v8, 0, v13
	v_mul_f32_e32 v13, v9, v9
	v_max_f32_e32 v9, 0, v14
	v_mul_f32_e32 v14, v10, v10
	v_max_f32_e32 v10, 0, v15
	v_mul_f32_e32 v12, v12, v12
	v_mul_f32_e32 v8, v8, v8
	v_max_f32_e32 v11, 0, v11
	v_mul_f32_e32 v9, v9, v9
	v_mul_f32_e32 v10, v10, v10
	v_cvt_pk_bf16_f32 v8, v12, v8
	v_add_co_u32_e32 v12, vcc, s75, v144
	v_max_f32_e32 v0, 0, v0
	v_max_f32_e32 v1, 0, v1
	v_max_f32_e32 v2, 0, v2
	v_mul_f32_e32 v11, v11, v11
	v_cvt_pk_bf16_f32 v9, v9, v10
	v_cvt_pk_bf16_f32 v10, v18, v13
	v_addc_co_u32_e32 v13, vcc, 0, v145, vcc
	v_cvt_pk_bf16_f32 v11, v14, v11
	global_store_dwordx4 v[12:13], v[8:11], off
	v_max_f32_e32 v3, 0, v3
	v_max_f32_e32 v4, 0, v4
	v_mul_f32_e32 v8, v0, v0
	v_max_f32_e32 v0, 0, v5
	v_mul_f32_e32 v5, v1, v1
	v_max_f32_e32 v1, 0, v6
	v_mul_f32_e32 v6, v2, v2
	v_max_f32_e32 v2, 0, v7
	v_lshl_add_u64 v[16:17], v[144:145], 0, s[56:57]
	v_mul_f32_e32 v0, v0, v0
	v_mul_f32_e32 v1, v1, v1
	v_mul_f32_e32 v2, v2, v2
	v_mul_f32_e32 v3, v3, v3
	s_and_b64 vcc, exec, s[8:9]
	s_mov_b64 s[8:9], -1
	v_mul_f32_e32 v4, v4, v4
	v_cvt_pk_bf16_f32 v0, v4, v0
	v_cvt_pk_bf16_f32 v1, v1, v2
	v_cvt_pk_bf16_f32 v2, v8, v5
	v_cvt_pk_bf16_f32 v3, v6, v3
	global_store_dwordx4 v[16:17], v[0:3], off offset:256
	s_cbranch_vccnz .LBB0_843
	s_andn2_b64 vcc, exec, s[42:43]
	s_cbranch_vccnz .LBB0_842
	s_barrier
	s_branch .LBB0_842
